# P2 rope epilogue path: 16 rope-table loads issued together at the path head into dead fragment registers, counted vmcnt(14) per row group instead of vmcnt(0) after each load pair
# baseline (speedup 1.0000x reference)
; #define GAS __attribute__((address_space(1)))
; __device__ __forceinline__ unsigned pk2(float lo, float hi) { return pg8::cvt_pk_bf16(lo, hi); }
;     __device__ __forceinline__ void operator()(const af4 (&acc)[2][2][4][2], const pg8::Unit& u, int wr, int wc, int fr, int fq) const {
;     ...
;         if (pn < 10 && u.pm < 64) {
;             const float qs = (pn < 8) ? 0.08838834764831845f * 1.4426950408889634f : 1.0f;
;             const int fbase = 16 * (wc & 1) + 4 * fq;
; #pragma unroll
;             for (int ai = 0; ai < 2; ++ai)
; #pragma unroll
;                 for (int m = 0; m < 4; ++m) {
;                     const int row = row0 + ai * 128 + m * 16, t = row & (SEQ - 1), pos = (wc < 2) ? (t >> 6) : (t & 63);
;                     const af4 cs = *(const GAS af4*)(rope + pos * 32 + fbase), sn = *(const GAS af4*)(rope + 4096 + pos * 32 + fbase);
;                     bf16* rowp = Z + (size_t)row * ZLD + col0;
; #pragma unroll
;                     for (int bj = 0; bj < 2; ++bj) {
;                         const af4 x1 = acc[ai][bj][m][0], x2 = acc[ai][bj][m][1];
;                         const af4 o1 = (x1 * cs - x2 * sn) * qs, o2 = (x2 * cs + x1 * sn) * qs;
;                         v4u w; w.x = pk2(o1[0], o1[1]); w.y = pk2(o1[2], o1[3]); w.z = pk2(o2[0], o2[1]); w.w = pk2(o2[2], o2[3]);
;                         *(GAS v4u*)(rowp + bj * 128) = w;
;                     }
.LBB0_408:
	s_cmp_lt_i32 s58, 8
	s_cselect_b64 vcc, -1, 0
	s_bfe_u32 s8, s19, 0x70006
	v_mov_b32_e32 v157, s8
	v_add_u32_e32 v246, 0x80, v173
	v_bfe_u32 v246, v246, 6, 7
	v_cndmask_b32_e64 v138, v1, v157, s[4:5]
	v_lshlrev_b32_e32 v138, 7, v138
	v_lshl_add_u64 v[250:251], v[142:143], 0, v[138:139]
	global_load_dwordx4 v[182:185], v[250:251], off
	v_lshl_add_u64 v[250:251], v[144:145], 0, v[138:139]
	global_load_dwordx4 v[186:189], v[250:251], off
	v_cndmask_b32_e64 v138, v166, v157, s[4:5]
	v_lshlrev_b32_e32 v138, 7, v138
	v_lshl_add_u64 v[250:251], v[142:143], 0, v[138:139]
	global_load_dwordx4 v[190:193], v[250:251], off
	v_lshl_add_u64 v[250:251], v[144:145], 0, v[138:139]
	global_load_dwordx4 v[194:197], v[250:251], off
	v_cndmask_b32_e64 v138, v167, v157, s[4:5]
	v_lshlrev_b32_e32 v138, 7, v138
	v_lshl_add_u64 v[250:251], v[142:143], 0, v[138:139]
	global_load_dwordx4 v[198:201], v[250:251], off
	v_lshl_add_u64 v[250:251], v[144:145], 0, v[138:139]
	global_load_dwordx4 v[202:205], v[250:251], off
	v_cndmask_b32_e64 v138, v168, v157, s[4:5]
	v_lshlrev_b32_e32 v138, 7, v138
	v_lshl_add_u64 v[250:251], v[142:143], 0, v[138:139]
	global_load_dwordx4 v[206:209], v[250:251], off
	v_lshl_add_u64 v[250:251], v[144:145], 0, v[138:139]
	global_load_dwordx4 v[210:213], v[250:251], off
	v_cndmask_b32_e64 v138, v1, v246, s[4:5]
	v_lshlrev_b32_e32 v138, 7, v138
	v_lshl_add_u64 v[250:251], v[142:143], 0, v[138:139]
	global_load_dwordx4 v[214:217], v[250:251], off
	v_lshl_add_u64 v[250:251], v[144:145], 0, v[138:139]
	global_load_dwordx4 v[218:221], v[250:251], off
	v_cndmask_b32_e64 v138, v166, v246, s[4:5]
	v_lshlrev_b32_e32 v138, 7, v138
	v_lshl_add_u64 v[250:251], v[142:143], 0, v[138:139]
	global_load_dwordx4 v[222:225], v[250:251], off
	v_lshl_add_u64 v[250:251], v[144:145], 0, v[138:139]
	global_load_dwordx4 v[226:229], v[250:251], off
	v_cndmask_b32_e64 v138, v167, v246, s[4:5]
	v_lshlrev_b32_e32 v138, 7, v138
	v_lshl_add_u64 v[250:251], v[142:143], 0, v[138:139]
	global_load_dwordx4 v[230:233], v[250:251], off
	v_lshl_add_u64 v[250:251], v[144:145], 0, v[138:139]
	global_load_dwordx4 v[234:237], v[250:251], off
	v_cndmask_b32_e64 v138, v168, v246, s[4:5]
	v_lshlrev_b32_e32 v138, 7, v138
	v_lshl_add_u64 v[250:251], v[142:143], 0, v[138:139]
	global_load_dwordx4 v[238:241], v[250:251], off
	v_lshl_add_u64 v[250:251], v[144:145], 0, v[138:139]
	global_load_dwordx4 v[242:245], v[250:251], off
	v_cndmask_b32_e64 v138, v1, v157, s[4:5]
	v_lshlrev_b32_e32 v138, 7, v138
	v_lshl_add_u64 v[158:159], v[142:143], 0, v[138:139]
	s_waitcnt vmcnt(14)
	v_mov_b64_e32 v[160:161], v[182:183]
	v_mov_b64_e32 v[162:163], v[184:185]
	v_lshl_add_u64 v[158:159], v[144:145], 0, v[138:139]
	v_mov_b64_e32 v[174:175], v[186:187]
	v_mov_b64_e32 v[176:177], v[188:189]
	v_cndmask_b32_e32 v156, 1.0, v172, vcc
	v_ashrrev_i32_e32 v155, 31, v154
	v_mov_b64_e32 v[158:159], s[50:51]
	v_mad_i64_i32 v[164:165], s[8:9], v173, s59, v[158:159]
	v_lshlrev_b64 v[154:155], 1, v[154:155]
	v_lshl_add_u64 v[164:165], v[164:165], 0, v[154:155]
	s_nop 0
	v_pk_mul_f32 v[178:179], v[124:125], v[176:177]
	v_pk_mul_f32 v[180:181], v[122:123], v[174:175]
	v_pk_fma_f32 v[178:179], v[128:129], v[162:163], v[178:179] neg_lo:[0,0,1] neg_hi:[0,0,1]
	v_pk_fma_f32 v[180:181], v[126:127], v[160:161], v[180:181] neg_lo:[0,0,1] neg_hi:[0,0,1]
	v_pk_mul_f32 v[128:129], v[128:129], v[176:177]
	v_pk_mul_f32 v[126:127], v[126:127], v[174:175]
	v_pk_fma_f32 v[124:125], v[124:125], v[162:163], v[128:129]
	v_pk_fma_f32 v[122:123], v[122:123], v[160:161], v[126:127]
	v_pk_mul_f32 v[126:127], v[156:157], v[124:125] op_sel_hi:[0,1]
	v_pk_mul_f32 v[124:125], v[156:157], v[122:123] op_sel_hi:[0,1]
	v_pk_mul_f32 v[178:179], v[156:157], v[178:179] op_sel_hi:[0,1]
	v_pk_mul_f32 v[180:181], v[156:157], v[180:181] op_sel_hi:[0,1]
	v_cvt_pk_bf16_f32 v122, v180, v181
	v_cvt_pk_bf16_f32 v123, v178, v179
	v_cvt_pk_bf16_f32 v124, v124, v125
	v_cvt_pk_bf16_f32 v125, v126, v127
	global_store_dwordx4 v[164:165], v[122:125], off
	s_nop 1
	v_pk_mul_f32 v[122:123], v[116:117], v[176:177]
	v_pk_mul_f32 v[124:125], v[114:115], v[174:175]
	v_pk_fma_f32 v[122:123], v[120:121], v[162:163], v[122:123] neg_lo:[0,0,1] neg_hi:[0,0,1]
	v_pk_fma_f32 v[124:125], v[118:119], v[160:161], v[124:125] neg_lo:[0,0,1] neg_hi:[0,0,1]
	v_pk_mul_f32 v[120:121], v[120:121], v[176:177]
	v_pk_mul_f32 v[118:119], v[118:119], v[174:175]
	v_pk_fma_f32 v[116:117], v[116:117], v[162:163], v[120:121]
	v_pk_fma_f32 v[114:115], v[114:115], v[160:161], v[118:119]
	v_pk_mul_f32 v[124:125], v[156:157], v[124:125] op_sel_hi:[0,1]
	v_pk_mul_f32 v[118:119], v[156:157], v[116:117] op_sel_hi:[0,1]
	v_pk_mul_f32 v[116:117], v[156:157], v[114:115] op_sel_hi:[0,1]
	v_cvt_pk_bf16_f32 v114, v124, v125
	v_pk_mul_f32 v[122:123], v[156:157], v[122:123] op_sel_hi:[0,1]
	v_cvt_pk_bf16_f32 v115, v122, v123
	v_cvt_pk_bf16_f32 v116, v116, v117
	v_cvt_pk_bf16_f32 v117, v118, v119
	global_store_dwordx4 v[164:165], v[114:117], off offset:256
	v_or_b32_e32 v122, 16, v173
	v_mad_i64_i32 v[122:123], s[8:9], v122, s59, v[158:159]
	v_cndmask_b32_e64 v114, v166, v157, s[4:5]
	v_lshlrev_b32_e32 v138, 7, v114
	v_lshl_add_u64 v[114:115], v[142:143], 0, v[138:139]
	v_lshl_add_u64 v[118:119], v[144:145], 0, v[138:139]
	s_waitcnt vmcnt(14)
; #define GAS __attribute__((address_space(1)))
; __device__ __forceinline__ unsigned pk2(float lo, float hi) { return pg8::cvt_pk_bf16(lo, hi); }
;     __device__ __forceinline__ void operator()(const af4 (&acc)[2][2][4][2], const pg8::Unit& u, int wr, int wc, int fr, int fq) const {
;     ...
;         if (pn < 10 && u.pm < 64) {
;             const float qs = (pn < 8) ? 0.08838834764831845f * 1.4426950408889634f : 1.0f;
;             const int fbase = 16 * (wc & 1) + 4 * fq;
; #pragma unroll
;             for (int ai = 0; ai < 2; ++ai)
; #pragma unroll
;                 for (int m = 0; m < 4; ++m) {
;                     const int row = row0 + ai * 128 + m * 16, t = row & (SEQ - 1), pos = (wc < 2) ? (t >> 6) : (t & 63);
;                     const af4 cs = *(const GAS af4*)(rope + pos * 32 + fbase), sn = *(const GAS af4*)(rope + 4096 + pos * 32 + fbase);
;                     bf16* rowp = Z + (size_t)row * ZLD + col0;
; #pragma unroll
;                     for (int bj = 0; bj < 2; ++bj) {
;                         const af4 x1 = acc[ai][bj][m][0], x2 = acc[ai][bj][m][1];
;                         const af4 o1 = (x1 * cs - x2 * sn) * qs, o2 = (x2 * cs + x1 * sn) * qs;
;                         v4u w; w.x = pk2(o1[0], o1[1]); w.y = pk2(o1[2], o1[3]); w.z = pk2(o2[0], o2[1]); w.w = pk2(o2[2], o2[3]);
;                         *(GAS v4u*)(rowp + bj * 128) = w;
;                     }
	v_mov_b64_e32 v[114:115], v[190:191]
	v_mov_b64_e32 v[116:117], v[192:193]
	v_lshl_add_u64 v[122:123], v[122:123], 0, v[154:155]
	v_mov_b64_e32 v[118:119], v[194:195]
	v_mov_b64_e32 v[120:121], v[196:197]
	s_nop 0
	v_pk_mul_f32 v[124:125], v[108:109], v[120:121]
	v_pk_mul_f32 v[126:127], v[106:107], v[118:119]
	v_pk_fma_f32 v[124:125], v[112:113], v[116:117], v[124:125] neg_lo:[0,0,1] neg_hi:[0,0,1]
	v_pk_fma_f32 v[126:127], v[110:111], v[114:115], v[126:127] neg_lo:[0,0,1] neg_hi:[0,0,1]
	v_pk_mul_f32 v[112:113], v[112:113], v[120:121]
	v_pk_mul_f32 v[110:111], v[110:111], v[118:119]
	v_pk_fma_f32 v[108:109], v[108:109], v[116:117], v[112:113]
	v_pk_fma_f32 v[106:107], v[106:107], v[114:115], v[110:111]
	v_pk_mul_f32 v[110:111], v[156:157], v[108:109] op_sel_hi:[0,1]
	v_pk_mul_f32 v[108:109], v[156:157], v[106:107] op_sel_hi:[0,1]
	v_pk_mul_f32 v[124:125], v[156:157], v[124:125] op_sel_hi:[0,1]
	v_pk_mul_f32 v[126:127], v[156:157], v[126:127] op_sel_hi:[0,1]
	v_cvt_pk_bf16_f32 v106, v126, v127
	v_cvt_pk_bf16_f32 v107, v124, v125
	v_cvt_pk_bf16_f32 v108, v108, v109
	v_cvt_pk_bf16_f32 v109, v110, v111
	global_store_dwordx4 v[122:123], v[106:109], off
	s_nop 1
	v_pk_mul_f32 v[106:107], v[100:101], v[120:121]
	v_pk_mul_f32 v[108:109], v[98:99], v[118:119]
	v_pk_fma_f32 v[106:107], v[104:105], v[116:117], v[106:107] neg_lo:[0,0,1] neg_hi:[0,0,1]
	v_pk_fma_f32 v[108:109], v[102:103], v[114:115], v[108:109] neg_lo:[0,0,1] neg_hi:[0,0,1]
	v_pk_mul_f32 v[104:105], v[104:105], v[120:121]
	v_pk_mul_f32 v[102:103], v[102:103], v[118:119]
	v_pk_fma_f32 v[100:101], v[100:101], v[116:117], v[104:105]
	v_pk_fma_f32 v[98:99], v[98:99], v[114:115], v[102:103]
	v_pk_mul_f32 v[108:109], v[156:157], v[108:109] op_sel_hi:[0,1]
	v_pk_mul_f32 v[102:103], v[156:157], v[100:101] op_sel_hi:[0,1]
	v_pk_mul_f32 v[100:101], v[156:157], v[98:99] op_sel_hi:[0,1]
	v_cvt_pk_bf16_f32 v98, v108, v109
	v_pk_mul_f32 v[106:107], v[156:157], v[106:107] op_sel_hi:[0,1]
	v_cvt_pk_bf16_f32 v99, v106, v107
	v_cvt_pk_bf16_f32 v100, v100, v101
	v_cvt_pk_bf16_f32 v101, v102, v103
	global_store_dwordx4 v[122:123], v[98:101], off offset:256
	v_or_b32_e32 v106, 32, v173
	v_mad_i64_i32 v[106:107], s[8:9], v106, s59, v[158:159]
	v_cndmask_b32_e64 v98, v167, v157, s[4:5]
	v_lshlrev_b32_e32 v138, 7, v98
	v_lshl_add_u64 v[98:99], v[142:143], 0, v[138:139]
	v_lshl_add_u64 v[102:103], v[144:145], 0, v[138:139]
	s_waitcnt vmcnt(14)
	v_mov_b64_e32 v[98:99], v[198:199]
	v_mov_b64_e32 v[100:101], v[200:201]
	v_lshl_add_u64 v[106:107], v[106:107], 0, v[154:155]
	v_mov_b64_e32 v[102:103], v[202:203]
	v_mov_b64_e32 v[104:105], v[204:205]
	s_nop 0
	v_pk_mul_f32 v[108:109], v[92:93], v[104:105]
	v_pk_mul_f32 v[110:111], v[90:91], v[102:103]
	v_pk_fma_f32 v[108:109], v[96:97], v[100:101], v[108:109] neg_lo:[0,0,1] neg_hi:[0,0,1]
	v_pk_fma_f32 v[110:111], v[94:95], v[98:99], v[110:111] neg_lo:[0,0,1] neg_hi:[0,0,1]
	v_pk_mul_f32 v[96:97], v[96:97], v[104:105]
	v_pk_mul_f32 v[94:95], v[94:95], v[102:103]
	v_pk_fma_f32 v[92:93], v[92:93], v[100:101], v[96:97]
	v_pk_fma_f32 v[90:91], v[90:91], v[98:99], v[94:95]
	v_pk_mul_f32 v[94:95], v[156:157], v[92:93] op_sel_hi:[0,1]
	v_pk_mul_f32 v[92:93], v[156:157], v[90:91] op_sel_hi:[0,1]
	v_pk_mul_f32 v[108:109], v[156:157], v[108:109] op_sel_hi:[0,1]
	v_pk_mul_f32 v[110:111], v[156:157], v[110:111] op_sel_hi:[0,1]
	v_cvt_pk_bf16_f32 v90, v110, v111
	v_cvt_pk_bf16_f32 v91, v108, v109
	v_cvt_pk_bf16_f32 v92, v92, v93
	v_cvt_pk_bf16_f32 v93, v94, v95
	global_store_dwordx4 v[106:107], v[90:93], off
	s_nop 1
	v_pk_mul_f32 v[90:91], v[84:85], v[104:105]
	v_pk_mul_f32 v[92:93], v[82:83], v[102:103]
	v_pk_fma_f32 v[90:91], v[88:89], v[100:101], v[90:91] neg_lo:[0,0,1] neg_hi:[0,0,1]
	v_pk_fma_f32 v[92:93], v[86:87], v[98:99], v[92:93] neg_lo:[0,0,1] neg_hi:[0,0,1]
	v_pk_mul_f32 v[88:89], v[88:89], v[104:105]
	v_pk_mul_f32 v[86:87], v[86:87], v[102:103]
	v_pk_fma_f32 v[84:85], v[84:85], v[100:101], v[88:89]
	v_pk_fma_f32 v[82:83], v[82:83], v[98:99], v[86:87]
	v_pk_mul_f32 v[92:93], v[156:157], v[92:93] op_sel_hi:[0,1]
	v_pk_mul_f32 v[86:87], v[156:157], v[84:85] op_sel_hi:[0,1]
	v_pk_mul_f32 v[84:85], v[156:157], v[82:83] op_sel_hi:[0,1]
	v_cvt_pk_bf16_f32 v82, v92, v93
	v_pk_mul_f32 v[90:91], v[156:157], v[90:91] op_sel_hi:[0,1]
	v_cvt_pk_bf16_f32 v83, v90, v91
	v_cvt_pk_bf16_f32 v84, v84, v85
	v_cvt_pk_bf16_f32 v85, v86, v87
	global_store_dwordx4 v[106:107], v[82:85], off offset:256
	v_or_b32_e32 v90, 48, v173
	v_mad_i64_i32 v[90:91], s[8:9], v90, s59, v[158:159]
	v_cndmask_b32_e64 v82, v168, v157, s[4:5]
	v_lshlrev_b32_e32 v138, 7, v82
	v_lshl_add_u64 v[82:83], v[142:143], 0, v[138:139]
	v_lshl_add_u64 v[86:87], v[144:145], 0, v[138:139]
	s_waitcnt vmcnt(14)
; #define GAS __attribute__((address_space(1)))
; __device__ __forceinline__ unsigned pk2(float lo, float hi) { return pg8::cvt_pk_bf16(lo, hi); }
;     __device__ __forceinline__ void operator()(const af4 (&acc)[2][2][4][2], const pg8::Unit& u, int wr, int wc, int fr, int fq) const {
;     ...
;         if (pn < 10 && u.pm < 64) {
;             const float qs = (pn < 8) ? 0.08838834764831845f * 1.4426950408889634f : 1.0f;
;             const int fbase = 16 * (wc & 1) + 4 * fq;
; #pragma unroll
;             for (int ai = 0; ai < 2; ++ai)
; #pragma unroll
;                 for (int m = 0; m < 4; ++m) {
;                     const int row = row0 + ai * 128 + m * 16, t = row & (SEQ - 1), pos = (wc < 2) ? (t >> 6) : (t & 63);
;                     const af4 cs = *(const GAS af4*)(rope + pos * 32 + fbase), sn = *(const GAS af4*)(rope + 4096 + pos * 32 + fbase);
;                     bf16* rowp = Z + (size_t)row * ZLD + col0;
; #pragma unroll
;                     for (int bj = 0; bj < 2; ++bj) {
;                         const af4 x1 = acc[ai][bj][m][0], x2 = acc[ai][bj][m][1];
;                         const af4 o1 = (x1 * cs - x2 * sn) * qs, o2 = (x2 * cs + x1 * sn) * qs;
;                         v4u w; w.x = pk2(o1[0], o1[1]); w.y = pk2(o1[2], o1[3]); w.z = pk2(o2[0], o2[1]); w.w = pk2(o2[2], o2[3]);
;                         *(GAS v4u*)(rowp + bj * 128) = w;
;                     }
	v_mov_b64_e32 v[82:83], v[206:207]
	v_mov_b64_e32 v[84:85], v[208:209]
	v_lshl_add_u64 v[90:91], v[90:91], 0, v[154:155]
	v_mov_b64_e32 v[86:87], v[210:211]
	v_mov_b64_e32 v[88:89], v[212:213]
	s_nop 0
	v_pk_mul_f32 v[92:93], v[76:77], v[88:89]
	v_pk_mul_f32 v[94:95], v[74:75], v[86:87]
	v_pk_fma_f32 v[92:93], v[80:81], v[84:85], v[92:93] neg_lo:[0,0,1] neg_hi:[0,0,1]
	v_pk_fma_f32 v[94:95], v[78:79], v[82:83], v[94:95] neg_lo:[0,0,1] neg_hi:[0,0,1]
	v_pk_mul_f32 v[80:81], v[80:81], v[88:89]
	v_pk_mul_f32 v[78:79], v[78:79], v[86:87]
	v_pk_fma_f32 v[76:77], v[76:77], v[84:85], v[80:81]
	v_pk_fma_f32 v[74:75], v[74:75], v[82:83], v[78:79]
	v_pk_mul_f32 v[78:79], v[156:157], v[76:77] op_sel_hi:[0,1]
	v_pk_mul_f32 v[76:77], v[156:157], v[74:75] op_sel_hi:[0,1]
	v_pk_mul_f32 v[92:93], v[156:157], v[92:93] op_sel_hi:[0,1]
	v_pk_mul_f32 v[94:95], v[156:157], v[94:95] op_sel_hi:[0,1]
	v_cvt_pk_bf16_f32 v74, v94, v95
	v_cvt_pk_bf16_f32 v75, v92, v93
	v_cvt_pk_bf16_f32 v76, v76, v77
	v_cvt_pk_bf16_f32 v77, v78, v79
	global_store_dwordx4 v[90:91], v[74:77], off
	s_nop 1
	v_pk_mul_f32 v[74:75], v[68:69], v[88:89]
	v_pk_mul_f32 v[76:77], v[66:67], v[86:87]
	v_pk_fma_f32 v[74:75], v[72:73], v[84:85], v[74:75] neg_lo:[0,0,1] neg_hi:[0,0,1]
	v_pk_fma_f32 v[76:77], v[70:71], v[82:83], v[76:77] neg_lo:[0,0,1] neg_hi:[0,0,1]
	v_pk_mul_f32 v[72:73], v[72:73], v[88:89]
	v_pk_mul_f32 v[70:71], v[70:71], v[86:87]
	v_pk_fma_f32 v[68:69], v[68:69], v[84:85], v[72:73]
	v_pk_fma_f32 v[66:67], v[66:67], v[82:83], v[70:71]
	v_pk_mul_f32 v[74:75], v[156:157], v[74:75] op_sel_hi:[0,1]
	v_pk_mul_f32 v[76:77], v[156:157], v[76:77] op_sel_hi:[0,1]
	v_pk_mul_f32 v[70:71], v[156:157], v[68:69] op_sel_hi:[0,1]
	v_pk_mul_f32 v[68:69], v[156:157], v[66:67] op_sel_hi:[0,1]
	v_cvt_pk_bf16_f32 v66, v76, v77
	v_cvt_pk_bf16_f32 v67, v74, v75
	v_cvt_pk_bf16_f32 v68, v68, v69
	v_cvt_pk_bf16_f32 v69, v70, v71
	global_store_dwordx4 v[90:91], v[66:69], off offset:256
	s_nop 1
	v_add_u32_e32 v67, 0x80, v173
	v_bfe_u32 v66, v67, 6, 7
	v_cndmask_b32_e64 v68, v1, v66, s[4:5]
	v_lshlrev_b32_e32 v138, 7, v68
	v_lshl_add_u64 v[68:69], v[142:143], 0, v[138:139]
	v_lshl_add_u64 v[72:73], v[144:145], 0, v[138:139]
	s_waitcnt vmcnt(14)
	v_mov_b64_e32 v[68:69], v[214:215]
	v_mov_b64_e32 v[70:71], v[216:217]
	v_mad_i64_i32 v[76:77], s[8:9], v67, s59, v[158:159]
	v_mov_b64_e32 v[72:73], v[218:219]
	v_mov_b64_e32 v[74:75], v[220:221]
	v_lshl_add_u64 v[76:77], v[76:77], 0, v[154:155]
	s_nop 0
	v_pk_mul_f32 v[78:79], v[60:61], v[74:75]
	v_pk_mul_f32 v[80:81], v[58:59], v[72:73]
	v_pk_fma_f32 v[78:79], v[64:65], v[70:71], v[78:79] neg_lo:[0,0,1] neg_hi:[0,0,1]
	v_pk_fma_f32 v[80:81], v[62:63], v[68:69], v[80:81] neg_lo:[0,0,1] neg_hi:[0,0,1]
	v_pk_mul_f32 v[64:65], v[64:65], v[74:75]
	v_pk_mul_f32 v[62:63], v[62:63], v[72:73]
	v_pk_fma_f32 v[60:61], v[60:61], v[70:71], v[64:65]
	v_pk_fma_f32 v[58:59], v[58:59], v[68:69], v[62:63]
	v_pk_mul_f32 v[62:63], v[156:157], v[60:61] op_sel_hi:[0,1]
	v_pk_mul_f32 v[60:61], v[156:157], v[58:59] op_sel_hi:[0,1]
	v_pk_mul_f32 v[78:79], v[156:157], v[78:79] op_sel_hi:[0,1]
	v_pk_mul_f32 v[80:81], v[156:157], v[80:81] op_sel_hi:[0,1]
	v_cvt_pk_bf16_f32 v58, v80, v81
	v_cvt_pk_bf16_f32 v59, v78, v79
	v_cvt_pk_bf16_f32 v60, v60, v61
	v_cvt_pk_bf16_f32 v61, v62, v63
	global_store_dwordx4 v[76:77], v[58:61], off
	s_nop 1
	v_pk_mul_f32 v[58:59], v[52:53], v[74:75]
	v_pk_mul_f32 v[60:61], v[50:51], v[72:73]
	v_pk_fma_f32 v[58:59], v[56:57], v[70:71], v[58:59] neg_lo:[0,0,1] neg_hi:[0,0,1]
	v_pk_fma_f32 v[60:61], v[54:55], v[68:69], v[60:61] neg_lo:[0,0,1] neg_hi:[0,0,1]
	v_pk_mul_f32 v[56:57], v[56:57], v[74:75]
	v_pk_mul_f32 v[54:55], v[54:55], v[72:73]
	v_pk_fma_f32 v[52:53], v[52:53], v[70:71], v[56:57]
	v_pk_fma_f32 v[50:51], v[50:51], v[68:69], v[54:55]
	v_pk_mul_f32 v[60:61], v[156:157], v[60:61] op_sel_hi:[0,1]
	v_pk_mul_f32 v[54:55], v[156:157], v[52:53] op_sel_hi:[0,1]
	v_pk_mul_f32 v[52:53], v[156:157], v[50:51] op_sel_hi:[0,1]
	v_cvt_pk_bf16_f32 v50, v60, v61
	v_pk_mul_f32 v[58:59], v[156:157], v[58:59] op_sel_hi:[0,1]
	v_cvt_pk_bf16_f32 v51, v58, v59
	v_cvt_pk_bf16_f32 v52, v52, v53
	v_cvt_pk_bf16_f32 v53, v54, v55
	global_store_dwordx4 v[76:77], v[50:53], off offset:256
	v_add_u32_e32 v58, 0x90, v173
	v_mad_i64_i32 v[58:59], s[8:9], v58, s59, v[158:159]
	v_cndmask_b32_e64 v50, v166, v66, s[4:5]
	v_lshlrev_b32_e32 v138, 7, v50
	v_lshl_add_u64 v[50:51], v[142:143], 0, v[138:139]
	v_lshl_add_u64 v[54:55], v[144:145], 0, v[138:139]
	s_waitcnt vmcnt(14)
; #define GAS __attribute__((address_space(1)))
; __device__ __forceinline__ unsigned pk2(float lo, float hi) { return pg8::cvt_pk_bf16(lo, hi); }
;     __device__ __forceinline__ void operator()(const af4 (&acc)[2][2][4][2], const pg8::Unit& u, int wr, int wc, int fr, int fq) const {
;     ...
;         if (pn < 10 && u.pm < 64) {
;             const float qs = (pn < 8) ? 0.08838834764831845f * 1.4426950408889634f : 1.0f;
;             const int fbase = 16 * (wc & 1) + 4 * fq;
; #pragma unroll
;             for (int ai = 0; ai < 2; ++ai)
; #pragma unroll
;                 for (int m = 0; m < 4; ++m) {
;                     const int row = row0 + ai * 128 + m * 16, t = row & (SEQ - 1), pos = (wc < 2) ? (t >> 6) : (t & 63);
;                     const af4 cs = *(const GAS af4*)(rope + pos * 32 + fbase), sn = *(const GAS af4*)(rope + 4096 + pos * 32 + fbase);
;                     bf16* rowp = Z + (size_t)row * ZLD + col0;
; #pragma unroll
;                     for (int bj = 0; bj < 2; ++bj) {
;                         const af4 x1 = acc[ai][bj][m][0], x2 = acc[ai][bj][m][1];
;                         const af4 o1 = (x1 * cs - x2 * sn) * qs, o2 = (x2 * cs + x1 * sn) * qs;
;                         v4u w; w.x = pk2(o1[0], o1[1]); w.y = pk2(o1[2], o1[3]); w.z = pk2(o2[0], o2[1]); w.w = pk2(o2[2], o2[3]);
;                         *(GAS v4u*)(rowp + bj * 128) = w;
;                     }
	v_mov_b64_e32 v[50:51], v[222:223]
	v_mov_b64_e32 v[52:53], v[224:225]
	v_lshl_add_u64 v[58:59], v[58:59], 0, v[154:155]
	v_mov_b64_e32 v[54:55], v[226:227]
	v_mov_b64_e32 v[56:57], v[228:229]
	s_nop 0
	v_pk_mul_f32 v[60:61], v[44:45], v[56:57]
	v_pk_mul_f32 v[62:63], v[42:43], v[54:55]
	v_pk_fma_f32 v[60:61], v[48:49], v[52:53], v[60:61] neg_lo:[0,0,1] neg_hi:[0,0,1]
	v_pk_fma_f32 v[62:63], v[46:47], v[50:51], v[62:63] neg_lo:[0,0,1] neg_hi:[0,0,1]
	v_pk_mul_f32 v[48:49], v[48:49], v[56:57]
	v_pk_mul_f32 v[46:47], v[46:47], v[54:55]
	v_pk_fma_f32 v[44:45], v[44:45], v[52:53], v[48:49]
	v_pk_fma_f32 v[42:43], v[42:43], v[50:51], v[46:47]
	v_pk_mul_f32 v[46:47], v[156:157], v[44:45] op_sel_hi:[0,1]
	v_pk_mul_f32 v[44:45], v[156:157], v[42:43] op_sel_hi:[0,1]
	v_pk_mul_f32 v[60:61], v[156:157], v[60:61] op_sel_hi:[0,1]
	v_pk_mul_f32 v[62:63], v[156:157], v[62:63] op_sel_hi:[0,1]
	v_cvt_pk_bf16_f32 v42, v62, v63
	v_cvt_pk_bf16_f32 v43, v60, v61
	v_cvt_pk_bf16_f32 v44, v44, v45
	v_cvt_pk_bf16_f32 v45, v46, v47
	global_store_dwordx4 v[58:59], v[42:45], off
	s_nop 1
	v_pk_mul_f32 v[42:43], v[36:37], v[56:57]
	v_pk_mul_f32 v[44:45], v[34:35], v[54:55]
	v_pk_fma_f32 v[42:43], v[40:41], v[52:53], v[42:43] neg_lo:[0,0,1] neg_hi:[0,0,1]
	v_pk_fma_f32 v[44:45], v[38:39], v[50:51], v[44:45] neg_lo:[0,0,1] neg_hi:[0,0,1]
	v_pk_mul_f32 v[40:41], v[40:41], v[56:57]
	v_pk_mul_f32 v[38:39], v[38:39], v[54:55]
	v_pk_fma_f32 v[36:37], v[36:37], v[52:53], v[40:41]
	v_pk_fma_f32 v[34:35], v[34:35], v[50:51], v[38:39]
	v_pk_mul_f32 v[44:45], v[156:157], v[44:45] op_sel_hi:[0,1]
	v_pk_mul_f32 v[38:39], v[156:157], v[36:37] op_sel_hi:[0,1]
	v_pk_mul_f32 v[36:37], v[156:157], v[34:35] op_sel_hi:[0,1]
	v_cvt_pk_bf16_f32 v34, v44, v45
	v_pk_mul_f32 v[42:43], v[156:157], v[42:43] op_sel_hi:[0,1]
	v_cvt_pk_bf16_f32 v35, v42, v43
	v_cvt_pk_bf16_f32 v36, v36, v37
	v_cvt_pk_bf16_f32 v37, v38, v39
	global_store_dwordx4 v[58:59], v[34:37], off offset:256
	v_add_u32_e32 v42, 0xa0, v173
	v_mad_i64_i32 v[42:43], s[8:9], v42, s59, v[158:159]
	v_cndmask_b32_e64 v34, v167, v66, s[4:5]
	v_lshlrev_b32_e32 v138, 7, v34
	v_lshl_add_u64 v[34:35], v[142:143], 0, v[138:139]
	v_lshl_add_u64 v[38:39], v[144:145], 0, v[138:139]
	s_waitcnt vmcnt(14)
	v_mov_b64_e32 v[34:35], v[230:231]
	v_mov_b64_e32 v[36:37], v[232:233]
	v_lshl_add_u64 v[42:43], v[42:43], 0, v[154:155]
	v_mov_b64_e32 v[38:39], v[234:235]
	v_mov_b64_e32 v[40:41], v[236:237]
	s_nop 0
	v_pk_mul_f32 v[44:45], v[28:29], v[40:41]
	v_pk_mul_f32 v[46:47], v[26:27], v[38:39]
	v_pk_fma_f32 v[44:45], v[32:33], v[36:37], v[44:45] neg_lo:[0,0,1] neg_hi:[0,0,1]
	v_pk_fma_f32 v[46:47], v[30:31], v[34:35], v[46:47] neg_lo:[0,0,1] neg_hi:[0,0,1]
	v_pk_mul_f32 v[32:33], v[32:33], v[40:41]
	v_pk_mul_f32 v[30:31], v[30:31], v[38:39]
	v_pk_fma_f32 v[28:29], v[28:29], v[36:37], v[32:33]
	v_pk_fma_f32 v[26:27], v[26:27], v[34:35], v[30:31]
	v_pk_mul_f32 v[30:31], v[156:157], v[28:29] op_sel_hi:[0,1]
	v_pk_mul_f32 v[28:29], v[156:157], v[26:27] op_sel_hi:[0,1]
	v_pk_mul_f32 v[44:45], v[156:157], v[44:45] op_sel_hi:[0,1]
	v_pk_mul_f32 v[46:47], v[156:157], v[46:47] op_sel_hi:[0,1]
	v_cvt_pk_bf16_f32 v26, v46, v47
	v_cvt_pk_bf16_f32 v27, v44, v45
	v_cvt_pk_bf16_f32 v28, v28, v29
	v_cvt_pk_bf16_f32 v29, v30, v31
	global_store_dwordx4 v[42:43], v[26:29], off
	s_nop 1
	v_pk_mul_f32 v[26:27], v[20:21], v[40:41]
	v_pk_mul_f32 v[28:29], v[18:19], v[38:39]
	v_pk_fma_f32 v[26:27], v[24:25], v[36:37], v[26:27] neg_lo:[0,0,1] neg_hi:[0,0,1]
	v_pk_fma_f32 v[28:29], v[22:23], v[34:35], v[28:29] neg_lo:[0,0,1] neg_hi:[0,0,1]
	v_pk_mul_f32 v[24:25], v[24:25], v[40:41]
	v_pk_mul_f32 v[22:23], v[22:23], v[38:39]
	v_pk_fma_f32 v[20:21], v[20:21], v[36:37], v[24:25]
	v_pk_fma_f32 v[18:19], v[18:19], v[34:35], v[22:23]
	v_pk_mul_f32 v[28:29], v[156:157], v[28:29] op_sel_hi:[0,1]
	v_pk_mul_f32 v[22:23], v[156:157], v[20:21] op_sel_hi:[0,1]
	v_pk_mul_f32 v[20:21], v[156:157], v[18:19] op_sel_hi:[0,1]
	v_cvt_pk_bf16_f32 v18, v28, v29
	v_pk_mul_f32 v[26:27], v[156:157], v[26:27] op_sel_hi:[0,1]
	v_cvt_pk_bf16_f32 v19, v26, v27
	v_cvt_pk_bf16_f32 v20, v20, v21
	v_cvt_pk_bf16_f32 v21, v22, v23
	global_store_dwordx4 v[42:43], v[18:21], off offset:256
	v_add_u32_e32 v26, 0xb0, v173
	v_mad_i64_i32 v[26:27], s[8:9], v26, s59, v[158:159]
	v_cndmask_b32_e64 v18, v168, v66, s[4:5]
	v_lshlrev_b32_e32 v138, 7, v18
	v_lshl_add_u64 v[18:19], v[142:143], 0, v[138:139]
	v_lshl_add_u64 v[22:23], v[144:145], 0, v[138:139]
	s_waitcnt vmcnt(14)
	v_mov_b64_e32 v[18:19], v[238:239]
	v_mov_b64_e32 v[20:21], v[240:241]
	v_lshl_add_u64 v[26:27], v[26:27], 0, v[154:155]
	v_mov_b64_e32 v[22:23], v[242:243]
	v_mov_b64_e32 v[24:25], v[244:245]
	s_nop 0
	v_pk_mul_f32 v[28:29], v[12:13], v[24:25]
	v_pk_mul_f32 v[30:31], v[10:11], v[22:23]
	v_pk_fma_f32 v[28:29], v[16:17], v[20:21], v[28:29] neg_lo:[0,0,1] neg_hi:[0,0,1]
	v_pk_fma_f32 v[30:31], v[14:15], v[18:19], v[30:31] neg_lo:[0,0,1] neg_hi:[0,0,1]
	v_pk_mul_f32 v[16:17], v[16:17], v[24:25]
	v_pk_mul_f32 v[14:15], v[14:15], v[22:23]
	v_pk_fma_f32 v[12:13], v[12:13], v[20:21], v[16:17]
	v_pk_fma_f32 v[10:11], v[10:11], v[18:19], v[14:15]
	v_pk_mul_f32 v[14:15], v[156:157], v[12:13] op_sel_hi:[0,1]
	v_pk_mul_f32 v[12:13], v[156:157], v[10:11] op_sel_hi:[0,1]
	v_pk_mul_f32 v[28:29], v[156:157], v[28:29] op_sel_hi:[0,1]
	v_pk_mul_f32 v[30:31], v[156:157], v[30:31] op_sel_hi:[0,1]
	v_cvt_pk_bf16_f32 v10, v30, v31
	v_cvt_pk_bf16_f32 v11, v28, v29
	v_cvt_pk_bf16_f32 v12, v12, v13
	v_cvt_pk_bf16_f32 v13, v14, v15
	global_store_dwordx4 v[26:27], v[10:13], off
	s_nop 1
	v_pk_mul_f32 v[10:11], v[4:5], v[24:25]
	v_pk_mul_f32 v[12:13], v[2:3], v[22:23]
	v_pk_fma_f32 v[10:11], v[8:9], v[20:21], v[10:11] neg_lo:[0,0,1] neg_hi:[0,0,1]
	v_pk_fma_f32 v[12:13], v[6:7], v[18:19], v[12:13] neg_lo:[0,0,1] neg_hi:[0,0,1]
	v_pk_mul_f32 v[8:9], v[8:9], v[24:25]
	v_pk_mul_f32 v[6:7], v[6:7], v[22:23]
	v_pk_fma_f32 v[4:5], v[4:5], v[20:21], v[8:9]
	v_pk_fma_f32 v[2:3], v[2:3], v[18:19], v[6:7]
	v_pk_mul_f32 v[6:7], v[156:157], v[4:5] op_sel_hi:[0,1]
	v_pk_mul_f32 v[4:5], v[156:157], v[2:3] op_sel_hi:[0,1]
	v_pk_mul_f32 v[10:11], v[156:157], v[10:11] op_sel_hi:[0,1]
	v_pk_mul_f32 v[12:13], v[156:157], v[12:13] op_sel_hi:[0,1]
	v_cvt_pk_bf16_f32 v2, v12, v13
	v_cvt_pk_bf16_f32 v3, v10, v11
	v_cvt_pk_bf16_f32 v4, v4, v5
	v_cvt_pk_bf16_f32 v5, v6, v7
	global_store_dwordx4 v[26:27], v[2:5], off offset:256
	s_andn2_b64 vcc, exec, s[6:7]
	s_mov_b64 s[6:7], -1
	s_cbranch_vccnz .LBB0_357
